# MLA attention: Q-fragment vmcnt waits hoisted out of the tile loop; K/V prefetch waited at its LDS stores
# speedup vs baseline: 1.0131x; 1.0131x over previous
.LBB0_555:
	s_lshl_b32 s2, s6, 4
	s_add_i32 s2, s7, s2
	s_ashr_i32 s3, s2, 4
	v_mov_b32_e32 v58, v163
	s_mul_i32 s2, s3, 0x1100
	v_readlane_b32 s4, v253, 36
	s_add_i32 s4, s4, s2
	v_and_b32_e32 v125, 15, v58
	v_ashrrev_i32_e32 v0, 1, v58
	v_bfe_u32 v59, v58, 4, 2
	v_and_b32_e32 v0, 0xffffffe0, v0
	s_waitcnt vmcnt(3)
	v_or_b32_e32 v2, s4, v125
	v_readlane_b32 s4, v254, 16
	v_add_u32_e32 v112, v2, v0
	v_lshlrev_b32_e32 v0, 4, v59
	v_readlane_b32 s5, v254, 17
	s_movk_i32 s8, 0xc00
	s_mulk_i32 s3, 0xef00
	v_lshl_add_u64 v[30:31], s[4:5], 0, v[0:1]
	s_waitcnt vmcnt(2)
	v_mad_i64_i32 v[6:7], s[4:5], v112, s8, v[30:31]
	s_waitcnt lgkmcnt(0)
	global_load_dwordx4 v[10:13], v[6:7], off offset:128
	s_addk_i32 s3, 0xff00
	v_add_u32_e32 v2, s3, v112
	v_ashrrev_i32_e32 v32, 6, v2
	v_and_b32_e32 v2, 47, v112
	v_cmp_gt_u32_e32 vcc, 2, v59
	v_readlane_b32 s40, v254, 55
	v_readlane_b32 s50, v255, 1
	v_cndmask_b32_e32 v2, v2, v32, vcc
	v_lshlrev_b32_e32 v2, 4, v2
	v_ashrrev_i32_e32 v3, 31, v2
	v_readlane_b32 s51, v255, 2
	v_cmp_lt_i32_e64 s[4:5], v198, v196
	v_or_b32_e32 v110, 16, v112
	v_lshl_add_u64 v[2:3], v[2:3], 2, s[50:51]
	global_load_dwordx4 v[14:17], v[2:3], off
	global_load_dwordx4 v[18:21], v[2:3], off offset:16
	global_load_dwordx4 v[22:25], v[2:3], off offset:32
	global_load_dwordx4 v[26:29], v[2:3], off offset:48
	v_cndmask_b32_e64 v2, v195, v198, s[4:5]
	v_mad_i64_i32 v[30:31], s[4:5], v110, s8, v[30:31]
	v_lshlrev_b32_e32 v124, 2, v2
	v_bitop3_b32 v33, v112, 63, 16 bitop3:0xc8
	global_load_dwordx4 v[2:5], v[6:7], off
	s_nop 0
	global_load_dwordx4 v[6:9], v[6:7], off offset:64
	v_cndmask_b32_e32 v32, v33, v32, vcc
	global_load_dwordx4 v[42:45], v[30:31], off offset:128
	v_lshlrev_b32_e32 v32, 4, v32
	v_ashrrev_i32_e32 v33, 31, v32
	v_lshl_add_u64 v[32:33], v[32:33], 2, s[50:51]
	global_load_dwordx4 v[38:41], v[32:33], off offset:48
	global_load_dwordx4 v[46:49], v[32:33], off offset:32
	global_load_dwordx4 v[50:53], v[32:33], off offset:16
	global_load_dwordx4 v[54:57], v[32:33], off
	v_and_b32_e32 v68, 16, v58
	v_cmp_eq_u32_e32 vcc, 0, v68
	v_ashrrev_i32_e32 v126, 3, v58
	v_readlane_b32 s4, v254, 18
	v_readlane_b32 s5, v254, 19
	v_readlane_b32 s8, v254, 36
	v_mov_b32_e32 v115, v1
	v_readlane_b32 s9, v254, 37
	v_ashrrev_i32_e32 v128, 2, v58
	v_readlane_b32 s41, v254, 56
	v_readlane_b32 s42, v254, 57
	v_readlane_b32 s43, v254, 58
	v_readlane_b32 s44, v254, 59
	v_readlane_b32 s45, v254, 60
	v_readlane_b32 s46, v254, 61
	v_readlane_b32 s47, v254, 62
	v_readlane_b32 s48, v254, 63
	v_readlane_b32 s49, v255, 0
	v_readlane_b32 s52, v255, 3
	v_readlane_b32 s53, v255, 4
	v_readlane_b32 s54, v255, 5
	v_readlane_b32 s55, v255, 6
	v_readlane_b32 s40, v252, 16
	v_readlane_b32 s42, v252, 18
	v_readlane_b32 s43, v252, 19
	v_mov_b32_e32 v117, v1
	s_waitcnt vmcnt(12)
	v_lshlrev_b32_e32 v131, 2, v59
	v_ashrrev_i32_e32 v113, 31, v112
	v_ashrrev_i32_e32 v111, 31, v110
	v_mov_b32_e32 v140, 0
	v_mov_b32_e32 v138, 0xf149f2ca
	v_mov_b32_e32 v139, 0xf149f2ca
	v_mov_b32_e32 v141, 0
	v_readlane_b32 s41, v252, 17
	v_readlane_b32 s44, v252, 20
	v_readlane_b32 s45, v252, 21
	v_readlane_b32 s46, v252, 22
	v_readlane_b32 s47, v252, 23
	v_readlane_b32 s48, v252, 24
	v_readlane_b32 s49, v252, 25
	v_readlane_b32 s50, v252, 26
	v_readlane_b32 s51, v252, 27
	v_readlane_b32 s52, v252, 28
	v_readlane_b32 s53, v252, 29
	v_readlane_b32 s54, v252, 30
	v_readlane_b32 s55, v252, 31
	s_waitcnt vmcnt(11)
	v_and_b32_e32 v33, 0xffff0000, v10
	v_lshlrev_b32_e32 v32, 16, v10
	v_and_b32_e32 v35, 0xffff0000, v11
	v_lshlrev_b32_e32 v34, 16, v11
	v_and_b32_e32 v11, 0xffff0000, v12
	v_lshlrev_b32_e32 v10, 16, v12
	v_and_b32_e32 v37, 0xffff0000, v13
	v_lshlrev_b32_e32 v36, 16, v13
	ds_bpermute_b32 v12, v124, v32
	ds_bpermute_b32 v13, v124, v33
	ds_bpermute_b32 v60, v124, v34
	ds_bpermute_b32 v61, v124, v35
	ds_bpermute_b32 v62, v124, v10
	ds_bpermute_b32 v63, v124, v11
	s_waitcnt vmcnt(10)
	v_mov_b32_e32 v67, v16
	v_mov_b32_e32 v16, v15
	s_waitcnt vmcnt(9)
	v_mov_b32_e32 v15, v20
	v_mov_b32_e32 v20, v19
	s_waitcnt vmcnt(8)
	v_mov_b32_e32 v19, v24
	v_mov_b32_e32 v24, v23
	s_waitcnt lgkmcnt(4)
	v_pk_mul_f32 v[12:13], v[16:17], v[12:13]
	s_waitcnt lgkmcnt(2)
	v_pk_mul_f32 v[16:17], v[20:21], v[60:61]
	ds_bpermute_b32 v64, v124, v36
	ds_bpermute_b32 v65, v124, v37
	v_mov_b32_e32 v66, v14
	v_mov_b32_e32 v14, v18
	s_waitcnt lgkmcnt(2)
	v_pk_mul_f32 v[20:21], v[24:25], v[62:63]
	v_cndmask_b32_e64 v17, v17, -v17, vcc
	v_cndmask_b32_e64 v16, v16, -v16, vcc
	v_mov_b32_e32 v18, v22
	v_cndmask_b32_e64 v13, v13, -v13, vcc
	v_cndmask_b32_e64 v12, v12, -v12, vcc
	v_cndmask_b32_e64 v21, v21, -v21, vcc
	v_cndmask_b32_e64 v20, v20, -v20, vcc
	v_pk_fma_f32 v[14:15], v[14:15], v[34:35], v[16:17]
	v_pk_fma_f32 v[12:13], v[66:67], v[32:33], v[12:13]
	v_pk_fma_f32 v[10:11], v[18:19], v[10:11], v[20:21]
	v_add_u32_e32 v60, s2, v126
	v_mov_b32_e32 v75, v15
	v_ashrrev_i32_e32 v61, 31, v60
	v_add_u32_e32 v18, 0x200, v58
	s_waitcnt vmcnt(7)
	v_mov_b32_e32 v23, v28
	v_mov_b32_e32 v28, v27
	v_mov_b32_e32 v72, v12
	v_mov_b32_e32 v74, v14
	v_lshlrev_b64 v[14:15], 11, v[60:61]
	v_lshlrev_b32_e32 v12, 4, v58
	v_ashrrev_i32_e32 v127, 3, v18
	s_waitcnt lgkmcnt(0)
	v_pk_mul_f32 v[24:25], v[28:29], v[64:65]
	v_mov_b32_e32 v76, v10
	v_mov_b32_e32 v77, v11
	v_lshl_add_u64 v[10:11], s[4:5], 0, v[14:15]
	v_and_b32_e32 v114, 0x70, v12
	v_add_u32_e32 v62, s2, v127
	v_mov_b32_e32 v22, v26
	v_cndmask_b32_e64 v25, v25, -v25, vcc
	v_cndmask_b32_e64 v24, v24, -v24, vcc
	v_lshl_add_u64 v[10:11], v[10:11], 0, v[114:115]
	v_lshl_add_u64 v[14:15], s[8:9], 0, v[14:15]
	v_ashrrev_i32_e32 v63, 31, v62
	v_pk_fma_f32 v[26:27], v[22:23], v[36:37], v[24:25]
	v_mov_b32_e32 v73, v13
	global_load_dwordx4 v[10:13], v[10:11], off
	v_lshl_add_u64 v[14:15], v[14:15], 0, v[114:115]
	v_lshlrev_b64 v[22:23], 11, v[62:63]
	v_add_u32_e32 v64, s2, v128
	v_lshlrev_b32_e32 v34, 3, v58
	global_load_dwordx4 v[14:17], v[14:15], off
	v_lshl_add_u64 v[18:19], s[4:5], 0, v[22:23]
	v_ashrrev_i32_e32 v65, 31, v64
	v_lshl_add_u64 v[18:19], v[18:19], 0, v[114:115]
	v_lshl_add_u64 v[22:23], s[8:9], 0, v[22:23]
	v_lshlrev_b64 v[28:29], 6, v[64:65]
	v_and_b32_e32 v130, 24, v34
	global_load_dwordx4 v[18:21], v[18:19], off
	v_lshl_add_u64 v[22:23], v[22:23], 0, v[114:115]
	v_lshl_add_u64 v[28:29], s[42:43], 0, v[28:29]
	v_lshlrev_b32_e32 v116, 1, v130
	global_load_dwordx4 v[22:25], v[22:23], off
	v_lshl_add_u64 v[28:29], v[28:29], 0, v[116:117]
	global_load_dwordx4 v[34:37], v[28:29], off
	v_mov_b32_e32 v61, v26
	v_mov_b32_e32 v63, v27
	global_load_dwordx4 v[26:29], v[30:31], off
	s_nop 0
	global_load_dwordx4 v[30:33], v[30:31], off offset:64
	s_waitcnt vmcnt(11)
	v_and_b32_e32 v67, 0xffff0000, v42
	v_lshlrev_b32_e32 v66, 16, v42
	ds_bpermute_b32 v68, v124, v66
	ds_bpermute_b32 v69, v124, v67
	s_waitcnt vmcnt(7)
	v_mov_b32_e32 v71, v56
	v_mov_b32_e32 v56, v55
	v_mov_b32_e32 v70, v54
	v_lshl_add_u64 v[118:119], s[4:5], 0, v[114:115]
	s_waitcnt lgkmcnt(0)
	v_pk_mul_f32 v[54:55], v[56:57], v[68:69]
	v_and_b32_e32 v57, 0xffff0000, v43
	v_lshlrev_b32_e32 v56, 16, v43
	ds_bpermute_b32 v42, v124, v56
	ds_bpermute_b32 v43, v124, v57
	v_cndmask_b32_e64 v55, v55, -v55, vcc
	v_cndmask_b32_e64 v54, v54, -v54, vcc
	v_pk_fma_f32 v[54:55], v[70:71], v[66:67], v[54:55]
	v_mov_b32_e32 v66, v50
	v_mov_b32_e32 v67, v52
	v_mov_b32_e32 v52, v51
	v_and_b32_e32 v51, 0xffff0000, v44
	v_lshlrev_b32_e32 v50, 16, v44
	s_waitcnt lgkmcnt(0)
	v_pk_mul_f32 v[42:43], v[52:53], v[42:43]
	ds_bpermute_b32 v52, v124, v50
	ds_bpermute_b32 v53, v124, v51
	v_cndmask_b32_e64 v43, v43, -v43, vcc
	v_cndmask_b32_e64 v42, v42, -v42, vcc
	v_pk_fma_f32 v[42:43], v[66:67], v[56:57], v[42:43]
	v_mov_b32_e32 v57, v48
	v_mov_b32_e32 v48, v47
	v_mov_b32_e32 v56, v46
	s_waitcnt lgkmcnt(0)
	v_pk_mul_f32 v[46:47], v[48:49], v[52:53]
	v_and_b32_e32 v49, 0xffff0000, v45
	v_lshlrev_b32_e32 v48, 16, v45
	ds_bpermute_b32 v44, v124, v48
	ds_bpermute_b32 v45, v124, v49
	v_cndmask_b32_e64 v47, v47, -v47, vcc
	v_cndmask_b32_e64 v46, v46, -v46, vcc
	v_pk_fma_f32 v[46:47], v[56:57], v[50:51], v[46:47]
	v_mov_b32_e32 v51, v40
	v_mov_b32_e32 v40, v39
	v_mov_b32_e32 v50, v38
	s_waitcnt lgkmcnt(0)
	v_pk_mul_f32 v[38:39], v[40:41], v[44:45]
	v_cndmask_b32_e64 v39, v39, -v39, vcc
	v_cndmask_b32_e64 v38, v38, -v38, vcc
	v_pk_fma_f32 v[38:39], v[50:51], v[48:49], v[38:39]
	v_mov_b32_e32 v44, v47
	v_mov_b32_e32 v45, v38
	v_mov_b32_e32 v47, v39
	v_mad_u64_u32 v[38:39], s[2:3], v126, s12, v[114:115]
	v_lshlrev_b32_e32 v39, 6, v126
	s_waitcnt vmcnt(6)
	ds_write_b128 v38, v[10:13]
	v_sub_u32_e32 v38, v38, v39
	v_cmp_lt_i32_e32 vcc, v197, v196
	s_waitcnt vmcnt(5)
	ds_write_b128 v38, v[14:17] offset:53248
	v_mad_u64_u32 v[38:39], s[2:3], v127, s12, v[114:115]
	v_lshlrev_b32_e32 v39, 6, v127
	s_waitcnt vmcnt(4)
	ds_write_b128 v38, v[18:21]
	v_sub_u32_e32 v38, v38, v39
	s_waitcnt vmcnt(3)
	ds_write_b128 v38, v[22:25] offset:53248
	v_mad_u64_u32 v[38:39], s[2:3], v128, s12, v[116:117]
	s_waitcnt vmcnt(2)
	ds_write_b128 v38, v[34:37] offset:128
	v_cndmask_b32_e32 v38, v195, v197, vcc
	v_lshlrev_b32_e32 v129, 2, v38
	v_bfe_u32 v38, v58, 2, 2
	v_mov_b32_e32 v48, v1
	v_mov_b32_e32 v49, v1
	v_or_b32_e32 v132, v131, v38
	v_cvt_pk_bf16_f32 v41, v61, v63
	v_cvt_pk_bf16_f32 v40, v76, v77
	v_cvt_pk_bf16_f32 v39, v74, v75
	v_cvt_pk_bf16_f32 v38, v72, v73
	v_cvt_pk_bf16_f32 v45, v45, v47
	v_cvt_pk_bf16_f32 v44, v46, v44
	v_cvt_pk_bf16_f32 v43, v42, v43
	v_cvt_pk_bf16_f32 v42, v54, v55
	v_lshl_add_u64 v[120:121], s[8:9], 0, v[114:115]
	v_lshl_add_u64 v[122:123], s[42:43], 0, v[116:117]
	v_add_u32_e32 v115, 0x80, v64
	v_add_u32_e32 v117, 0x80, v62
	v_add_u32_e32 v137, 0x80, v60
	v_mov_b32_e32 v46, v1
	v_mov_b32_e32 v47, v1
	v_mov_b64_e32 v[64:65], v[48:49]
	v_mov_b64_e32 v[52:53], v[48:49]
	v_mov_b64_e32 v[68:69], v[48:49]
	v_mov_b64_e32 v[56:57], v[48:49]
	v_mov_b64_e32 v[72:73], v[48:49]
	v_mov_b64_e32 v[60:61], v[48:49]
	v_mov_b64_e32 v[76:77], v[48:49]
	v_or_b32_e32 v133, 0xd000, v130
	v_or_b32_e32 v134, 0xd020, v130
	v_or_b32_e32 v135, 0xd040, v130
	v_or_b32_e32 v136, 0xd060, v130
	s_mov_b32 s4, 0
	v_mov_b64_e32 v[62:63], v[46:47]
	v_mov_b64_e32 v[50:51], v[46:47]
	v_mov_b64_e32 v[66:67], v[46:47]
	v_mov_b64_e32 v[54:55], v[46:47]
	v_mov_b64_e32 v[70:71], v[46:47]
	v_mov_b64_e32 v[58:59], v[46:47]
	v_mov_b64_e32 v[74:75], v[46:47]
	s_waitcnt vmcnt(0)
	s_waitcnt lgkmcnt(0)
	s_barrier
	s_branch .LBB0_557

.LBB0_559:
	s_and_b32 s5, s4, 0x80
	v_or_b32_e32 v142, s5, v125
	v_mad_u32_u24 v143, v142, s12, v0
	ds_read_b128 v[78:81], v143
	ds_read_b128 v[82:85], v143 offset:64
	ds_read_b128 v[86:89], v143 offset:128
	ds_read_b128 v[94:97], v143 offset:3328
	ds_read_b128 v[98:101], v143 offset:3392
	ds_read_b128 v[144:147], v143 offset:3456
	s_setprio 1
	s_waitcnt lgkmcnt(5)
	v_mfma_f32_16x16x32_bf16 v[90:93], v[78:81], v[2:5], 0
	v_mfma_f32_16x16x32_bf16 v[78:81], v[78:81], v[26:29], 0
	s_waitcnt lgkmcnt(4)
	v_mfma_f32_16x16x32_bf16 v[90:93], v[82:85], v[6:9], v[90:93]
	v_mfma_f32_16x16x32_bf16 v[78:81], v[82:85], v[30:33], v[78:81]
	s_waitcnt lgkmcnt(3)
	v_mfma_f32_16x16x32_bf16 v[106:109], v[86:89], v[38:41], v[90:93]
	v_mfma_f32_16x16x32_bf16 v[90:93], v[86:89], v[42:45], v[78:81]
	s_waitcnt lgkmcnt(2)
	v_mfma_f32_16x16x32_bf16 v[78:81], v[94:97], v[2:5], 0
	v_mfma_f32_16x16x32_bf16 v[82:85], v[94:97], v[26:29], 0
	s_waitcnt lgkmcnt(1)
	v_mfma_f32_16x16x32_bf16 v[78:81], v[98:101], v[6:9], v[78:81]
	v_mfma_f32_16x16x32_bf16 v[82:85], v[98:101], v[30:33], v[82:85]
	s_waitcnt lgkmcnt(0)
	v_mfma_f32_16x16x32_bf16 v[102:105], v[144:147], v[38:41], v[78:81]
	v_mfma_f32_16x16x32_bf16 v[82:85], v[144:147], v[42:45], v[82:85]
	s_setprio 0
	s_nop 2
	ds_read_b128 v[78:81], v143 offset:6656
	ds_read_b128 v[86:89], v143 offset:6720
	ds_read_b128 v[94:97], v143 offset:6784
	ds_read_b128 v[144:147], v143 offset:9984
	ds_read_b128 v[148:151], v143 offset:10048
	ds_read_b128 v[152:155], v143 offset:10112
	s_setprio 1
	s_waitcnt lgkmcnt(5)
	v_mfma_f32_16x16x32_bf16 v[98:101], v[78:81], v[2:5], 0
	v_mfma_f32_16x16x32_bf16 v[78:81], v[78:81], v[26:29], 0
	s_waitcnt lgkmcnt(4)
	v_mfma_f32_16x16x32_bf16 v[98:101], v[86:89], v[6:9], v[98:101]
	v_mfma_f32_16x16x32_bf16 v[78:81], v[86:89], v[30:33], v[78:81]
	s_waitcnt lgkmcnt(3)
	v_mfma_f32_16x16x32_bf16 v[98:101], v[94:97], v[38:41], v[98:101]
	v_mfma_f32_16x16x32_bf16 v[86:89], v[94:97], v[42:45], v[78:81]
	s_waitcnt lgkmcnt(2)
	v_mfma_f32_16x16x32_bf16 v[78:81], v[144:147], v[2:5], 0
	v_mfma_f32_16x16x32_bf16 v[94:97], v[144:147], v[26:29], 0
	s_waitcnt lgkmcnt(1)
	v_mfma_f32_16x16x32_bf16 v[78:81], v[148:151], v[6:9], v[78:81]
	v_mfma_f32_16x16x32_bf16 v[144:147], v[148:151], v[30:33], v[94:97]
	s_waitcnt lgkmcnt(0)
	v_mfma_f32_16x16x32_bf16 v[94:97], v[152:155], v[38:41], v[78:81]
	v_mfma_f32_16x16x32_bf16 v[78:81], v[152:155], v[42:45], v[144:147]
	s_setprio 0
	v_max3_f32 v143, v106, s18, v107
	v_max3_f32 v143, v143, v108, v109
	v_max3_f32 v143, v143, v102, v103
	v_max3_f32 v143, v143, v104, v105
	v_max3_f32 v143, v143, v98, v99
	v_max3_f32 v143, v143, v100, v101
	v_max3_f32 v143, v143, v94, v95
	v_max3_f32 v143, v143, v96, v97
	v_mul_f32_e32 v143, 0x3e16c740, v143
	ds_bpermute_b32 v144, v124, v143
	s_waitcnt lgkmcnt(0)
	v_max_f32_e32 v144, v144, v144
	v_max_f32_e32 v143, v143, v144
	ds_bpermute_b32 v144, v129, v143
	s_waitcnt lgkmcnt(0)
	v_max_f32_e32 v144, v144, v144
	v_max_f32_e32 v143, v143, v144
	v_add_f32_e32 v144, 0x41000000, v139
	v_cmp_gt_f32_e32 vcc, v143, v144
	s_cbranch_vccz .LBB0_561
	v_max_f32_e32 v143, v143, v143
	v_max_f32_e32 v144, v139, v139
	v_max_f32_e32 v143, v144, v143
	v_sub_f32_e32 v139, v139, v143
	v_exp_f32_e32 v144, v139
	v_mov_b32_e32 v139, v143
	v_mul_f32_e32 v141, v141, v144
	v_pk_mul_f32 v[76:77], v[76:77], v[144:145] op_sel_hi:[1,0]
	v_pk_mul_f32 v[74:75], v[74:75], v[144:145] op_sel_hi:[1,0]
	v_pk_mul_f32 v[72:73], v[72:73], v[144:145] op_sel_hi:[1,0]
	v_pk_mul_f32 v[70:71], v[70:71], v[144:145] op_sel_hi:[1,0]
	v_pk_mul_f32 v[68:69], v[68:69], v[144:145] op_sel_hi:[1,0]
	v_pk_mul_f32 v[66:67], v[66:67], v[144:145] op_sel_hi:[1,0]
	v_pk_mul_f32 v[64:65], v[64:65], v[144:145] op_sel_hi:[1,0]
	v_pk_mul_f32 v[62:63], v[62:63], v[144:145] op_sel_hi:[1,0]

.LBB0_569:
	v_lshl_add_u32 v180, v143, 1, v210
	v_fmamk_f32 v106, v106, 0x3e16c740, v160
	v_fmamk_f32 v107, v107, 0x3e16c740, v160
	v_fmamk_f32 v108, v108, 0x3e16c740, v160
	v_fmamk_f32 v109, v109, 0x3e16c740, v160
	v_fmamk_f32 v98, v98, 0x3e16c740, v160
	v_fmamk_f32 v99, v99, 0x3e16c740, v160
	v_fmamk_f32 v100, v100, 0x3e16c740, v160
	v_fmamk_f32 v101, v101, 0x3e16c740, v160
	v_fmamk_f32 v102, v102, 0x3e16c740, v160
	v_fmamk_f32 v103, v103, 0x3e16c740, v160
	v_fmamk_f32 v104, v104, 0x3e16c740, v160
	v_fmamk_f32 v105, v105, 0x3e16c740, v160
	v_fmamk_f32 v94, v94, 0x3e16c740, v160
	v_fmamk_f32 v95, v95, 0x3e16c740, v160
	v_fmamk_f32 v96, v96, 0x3e16c740, v160
	v_fmac_f32_e32 v160, 0x3e16c740, v97
	v_fmamk_f32 v90, v90, 0x3e16c740, v144
	v_fmamk_f32 v91, v91, 0x3e16c740, v144
	v_fmamk_f32 v92, v92, 0x3e16c740, v144
	v_fmamk_f32 v93, v93, 0x3e16c740, v144
	v_fmamk_f32 v82, v82, 0x3e16c740, v144
	v_fmamk_f32 v83, v83, 0x3e16c740, v144
	v_fmamk_f32 v84, v84, 0x3e16c740, v144
	v_fmamk_f32 v85, v85, 0x3e16c740, v144
	v_fmamk_f32 v86, v86, 0x3e16c740, v144
	v_fmamk_f32 v87, v87, 0x3e16c740, v144
	v_fmamk_f32 v88, v88, 0x3e16c740, v144
	v_fmamk_f32 v89, v89, 0x3e16c740, v144
	v_fmamk_f32 v78, v78, 0x3e16c740, v144
	v_fmamk_f32 v79, v79, 0x3e16c740, v144
	v_fmamk_f32 v80, v80, 0x3e16c740, v144
	v_fmac_f32_e32 v144, 0x3e16c740, v81
	v_add_u32_e32 v143, v133, v180
	v_exp_f32_e32 v97, v160
	v_exp_f32_e32 v81, v144
	ds_read_b64_tr_b16 v[160:161], v142 offset:64768
	ds_read_b64_tr_b16 v[158:159], v142 offset:62464
	ds_read_b64_tr_b16 v[166:167], v142 offset:64800
	ds_read_b64_tr_b16 v[164:165], v142 offset:62496
	v_add_u32_e32 v144, v134, v180
	ds_read_b64_tr_b16 v[168:169], v143
	ds_read_b64_tr_b16 v[170:171], v143 offset:2304
	ds_read_b64_tr_b16 v[172:173], v144
	ds_read_b64_tr_b16 v[174:175], v144 offset:2304
	v_exp_f32_e32 v106, v106
	v_exp_f32_e32 v107, v107
	v_exp_f32_e32 v108, v108
	v_exp_f32_e32 v109, v109
	v_exp_f32_e32 v98, v98
	v_exp_f32_e32 v99, v99
	v_exp_f32_e32 v100, v100
	v_exp_f32_e32 v101, v101
	v_exp_f32_e32 v102, v102
	v_exp_f32_e32 v103, v103
	v_exp_f32_e32 v104, v104
	v_exp_f32_e32 v105, v105
	v_exp_f32_e32 v94, v94
	v_exp_f32_e32 v95, v95
	v_exp_f32_e32 v96, v96
	v_exp_f32_e32 v90, v90
	v_exp_f32_e32 v91, v91
	v_exp_f32_e32 v92, v92
	v_exp_f32_e32 v93, v93
	v_exp_f32_e32 v82, v82
	v_exp_f32_e32 v83, v83
	v_exp_f32_e32 v84, v84
	v_exp_f32_e32 v85, v85
	v_exp_f32_e32 v86, v86
	v_exp_f32_e32 v87, v87
	v_exp_f32_e32 v88, v88
	v_exp_f32_e32 v89, v89
	v_exp_f32_e32 v78, v78
	v_exp_f32_e32 v79, v79
	v_exp_f32_e32 v80, v80
	v_cvt_pk_bf16_f32 v146, v106, v107
	v_cvt_pk_bf16_f32 v147, v108, v109
	v_cvt_pk_bf16_f32 v148, v98, v99
	v_cvt_pk_bf16_f32 v149, v100, v101
	v_cvt_pk_bf16_f32 v150, v102, v103
	v_cvt_pk_bf16_f32 v151, v104, v105
	v_cvt_pk_bf16_f32 v152, v94, v95
	v_cvt_pk_bf16_f32 v153, v96, v97
	v_cvt_pk_bf16_f32 v154, v90, v91
	v_cvt_pk_bf16_f32 v155, v92, v93
	v_cvt_pk_bf16_f32 v156, v82, v83
	v_cvt_pk_bf16_f32 v157, v84, v85
	v_cvt_pk_bf16_f32 v176, v86, v87
	v_cvt_pk_bf16_f32 v177, v88, v89
	v_cvt_pk_bf16_f32 v178, v78, v79
	v_cvt_pk_bf16_f32 v179, v80, v81
	s_setprio 1
	s_waitcnt lgkmcnt(6)
	v_mfma_f32_16x16x32_bf16 v[74:77], v[158:161], v[146:149], v[74:77]
	v_mfma_f32_16x16x32_bf16 v[58:61], v[158:161], v[154:157], v[58:61]
	s_waitcnt lgkmcnt(4)
	v_mfma_f32_16x16x32_bf16 v[54:57], v[164:167], v[146:149], v[54:57]
	v_mfma_f32_16x16x32_bf16 v[158:161], v[164:167], v[154:157], v[70:73]
	s_waitcnt lgkmcnt(2)
	v_mfma_f32_16x16x32_bf16 v[74:77], v[168:171], v[150:153], v[74:77]
	v_mfma_f32_16x16x32_bf16 v[58:61], v[168:171], v[176:179], v[58:61]
	s_waitcnt lgkmcnt(0)
	v_mfma_f32_16x16x32_bf16 v[70:73], v[172:175], v[150:153], v[54:57]
	v_mfma_f32_16x16x32_bf16 v[54:57], v[172:175], v[176:179], v[158:161]
	s_setprio 0
	v_add_u32_e32 v166, v135, v180
	v_add_u32_e32 v170, v136, v180
	ds_read_b64_tr_b16 v[160:161], v142 offset:64832
	ds_read_b64_tr_b16 v[158:159], v142 offset:62528
	ds_read_b64_tr_b16 v[144:145], v142 offset:64864
	ds_read_b64_tr_b16 v[142:143], v142 offset:62560
	ds_read_b64_tr_b16 v[164:165], v166
	ds_read_b64_tr_b16 v[166:167], v166 offset:2304
	ds_read_b64_tr_b16 v[168:169], v170
	ds_read_b64_tr_b16 v[170:171], v170 offset:2304
	s_setprio 1
	s_waitcnt lgkmcnt(6)
	v_mfma_f32_16x16x32_bf16 v[50:53], v[158:161], v[146:149], v[50:53]
	v_mfma_f32_16x16x32_bf16 v[158:161], v[158:161], v[154:157], v[66:69]
	s_waitcnt lgkmcnt(4)
	v_mfma_f32_16x16x32_bf16 v[46:49], v[142:145], v[146:149], v[46:49]
	v_mfma_f32_16x16x32_bf16 v[142:145], v[142:145], v[154:157], v[62:65]
	s_waitcnt lgkmcnt(2)
	v_mfma_f32_16x16x32_bf16 v[66:69], v[164:167], v[150:153], v[50:53]
	v_mfma_f32_16x16x32_bf16 v[50:53], v[164:167], v[176:179], v[158:161]
	s_waitcnt lgkmcnt(0)
	v_mfma_f32_16x16x32_bf16 v[62:65], v[168:171], v[150:153], v[46:49]
	v_mfma_f32_16x16x32_bf16 v[46:49], v[168:171], v[176:179], v[142:145]
	s_setprio 0
	s_andn2_b64 vcc, exec, s[2:3]
	s_cbranch_vccnz .LBB0_556
	s_xor_b32 s5, s5, 0x80
	v_add_u32_e32 v144, s5, v126
	v_mad_u64_u32 v[142:143], s[2:3], v144, s12, v[114:115]
	s_waitcnt vmcnt(4)
	ds_write_b128 v142, v[10:13]
	v_mad_u64_u32 v[142:143], s[2:3], v144, s16, v[114:115]
	v_add_u32_e32 v144, s5, v127
	s_waitcnt vmcnt(3)
	ds_write_b128 v142, v[14:17] offset:53248
	v_mad_u64_u32 v[142:143], s[2:3], v144, s12, v[114:115]
	s_waitcnt vmcnt(2)
	ds_write_b128 v142, v[18:21]
	v_mad_u64_u32 v[142:143], s[2:3], v144, s16, v[114:115]
	s_waitcnt vmcnt(1)
	ds_write_b128 v142, v[22:25] offset:53248
	v_add_u32_e32 v142, s5, v128
	v_mad_u64_u32 v[142:143], s[2:3], v142, s12, v[116:117]
	s_waitcnt vmcnt(0)
	ds_write_b128 v142, v[34:37] offset:128
	s_branch .LBB0_556

.LBB0_572:
	s_ashr_i32 s7, s6, 8
	s_lshl_b32 s4, s6, 8
	s_mul_i32 s3, s7, 0x1100
	s_and_b32 s4, s4, 0xf00
	v_mov_b32_e32 v50, v163
	s_add_i32 s4, s3, s4
	s_bfe_u32 s2, s6, 0x40004
	v_and_b32_e32 v125, 15, v50
	s_addk_i32 s4, 0x100
	v_readlane_b32 s52, v254, 20
	v_ashrrev_i32_e32 v0, 1, v50
	s_waitcnt vmcnt(3)
	v_or_b32_e32 v2, s4, v125
	s_mul_i32 s4, s2, 0xc0
	v_readlane_b32 s60, v254, 28
	v_bfe_u32 v51, v50, 4, 2
	v_and_b32_e32 v0, 0xffffffe0, v0
	v_readlane_b32 s61, v254, 29
	s_add_u32 s4, s60, s4
	v_add_u32_e32 v112, v2, v0
	s_addc_u32 s5, s61, 0
	v_lshlrev_b32_e32 v0, 4, v51
	v_lshl_add_u64 v[2:3], s[4:5], 0, v[0:1]
	s_movk_i32 s8, 0xc00
	s_waitcnt vmcnt(2)
	v_mad_i64_i32 v[6:7], s[4:5], v112, s8, v[2:3]
	s_mul_i32 s4, s7, 0xffffef00
	s_addk_i32 s4, 0xff00
	global_load_dwordx4 v[14:17], v[6:7], off offset:128
	v_add_u32_e32 v4, s4, v112
	v_ashrrev_i32_e32 v32, 6, v4
	v_and_b32_e32 v4, 47, v112
	v_cmp_gt_u32_e32 vcc, 2, v51
	v_cmp_lt_i32_e64 s[4:5], v198, v196
	v_or_b32_e32 v110, 16, v112
	v_cndmask_b32_e32 v4, v4, v32, vcc
	v_lshlrev_b32_e32 v4, 4, v4
	v_ashrrev_i32_e32 v5, 31, v4
	v_lshl_add_u64 v[4:5], v[4:5], 2, s[50:51]
	global_load_dwordx4 v[18:21], v[4:5], off
	global_load_dwordx4 v[22:25], v[4:5], off offset:16
	global_load_dwordx4 v[26:29], v[4:5], off offset:32
	s_waitcnt lgkmcnt(0)
	global_load_dwordx4 v[10:13], v[4:5], off offset:48
	v_cndmask_b32_e64 v4, v195, v198, s[4:5]
	v_lshlrev_b32_e32 v124, 2, v4
	v_bitop3_b32 v33, v112, 63, 16 bitop3:0xc8
	v_mad_i64_i32 v[30:31], s[4:5], v110, s8, v[2:3]
	global_load_dwordx4 v[2:5], v[6:7], off
	s_nop 0
	global_load_dwordx4 v[6:9], v[6:7], off offset:64
	s_nop 0
	global_load_dwordx4 v[38:41], v[30:31], off offset:128
	v_cndmask_b32_e32 v32, v33, v32, vcc
	v_lshlrev_b32_e32 v32, 4, v32
	v_ashrrev_i32_e32 v33, 31, v32
	v_lshl_add_u64 v[32:33], v[32:33], 2, s[50:51]
	global_load_dwordx4 v[42:45], v[32:33], off offset:16
	global_load_dwordx4 v[46:49], v[32:33], off
	v_and_b32_e32 v62, 16, v50
	v_cmp_eq_u32_e32 vcc, 0, v62
	v_ashrrev_i32_e32 v126, 3, v50
	v_readlane_b32 s62, v254, 30
	v_readlane_b32 s63, v254, 31
	v_readlane_b32 s64, v254, 32
	v_readlane_b32 s65, v254, 33
	s_lshl_b32 s34, s2, 7
	v_mov_b32_e32 v115, v1
	v_ashrrev_i32_e32 v129, 2, v50
	v_readlane_b32 s53, v254, 21
	v_readlane_b32 s54, v254, 22
	v_readlane_b32 s55, v254, 23
	v_add_u32_e32 v64, s3, v129
	v_ashrrev_i32_e32 v65, 31, v64
	v_readlane_b32 s40, v252, 16
	v_readlane_b32 s42, v252, 18
	v_readlane_b32 s43, v252, 19
	v_mov_b32_e32 v117, v1
	s_lshl_b32 s4, s2, 6
	s_waitcnt vmcnt(10)
	v_lshlrev_b32_e32 v131, 2, v51
	s_mov_b32 s7, 0
	v_ashrrev_i32_e32 v113, 31, v112
	v_ashrrev_i32_e32 v111, 31, v110
	v_mov_b32_e32 v140, 0
	v_mov_b32_e32 v138, 0xf149f2ca
	v_mov_b32_e32 v139, 0xf149f2ca
	v_mov_b32_e32 v141, 0
	v_readlane_b32 s56, v254, 24
	v_readlane_b32 s57, v254, 25
	v_readlane_b32 s58, v254, 26
	v_readlane_b32 s59, v254, 27
	v_readlane_b32 s66, v254, 34
	v_readlane_b32 s67, v254, 35
	v_readlane_b32 s41, v252, 17
	v_readlane_b32 s44, v252, 20
	v_readlane_b32 s45, v252, 21
	v_readlane_b32 s46, v252, 22
	v_readlane_b32 s47, v252, 23
	v_readlane_b32 s48, v252, 24
	v_readlane_b32 s49, v252, 25
	v_readlane_b32 s50, v252, 26
	v_readlane_b32 s51, v252, 27
	v_readlane_b32 s52, v252, 28
	v_readlane_b32 s53, v252, 29
	v_readlane_b32 s54, v252, 30
	v_readlane_b32 s55, v252, 31
	s_waitcnt vmcnt(9)
	v_and_b32_e32 v35, 0xffff0000, v14
	v_lshlrev_b32_e32 v34, 16, v14
	v_and_b32_e32 v37, 0xffff0000, v15
	v_lshlrev_b32_e32 v36, 16, v15
	v_and_b32_e32 v15, 0xffff0000, v16
	v_lshlrev_b32_e32 v14, 16, v16
	v_and_b32_e32 v53, 0xffff0000, v17
	v_lshlrev_b32_e32 v52, 16, v17
	ds_bpermute_b32 v16, v124, v34
	ds_bpermute_b32 v17, v124, v35
	ds_bpermute_b32 v56, v124, v14
	ds_bpermute_b32 v57, v124, v15
	ds_bpermute_b32 v54, v124, v36
	ds_bpermute_b32 v55, v124, v37
	ds_bpermute_b32 v58, v124, v52
	ds_bpermute_b32 v59, v124, v53
	s_waitcnt vmcnt(8)
	v_mov_b32_e32 v61, v20
	v_mov_b32_e32 v20, v19
	s_waitcnt vmcnt(7)
	v_mov_b32_e32 v19, v24
	v_mov_b32_e32 v24, v23
	s_waitcnt vmcnt(6)
	v_mov_b32_e32 v23, v28
	v_mov_b32_e32 v28, v27
	v_mov_b32_e32 v60, v18
	v_mov_b32_e32 v18, v22
	v_mov_b32_e32 v22, v26
	s_waitcnt vmcnt(5)
	v_mov_b32_e32 v26, v10
	v_mov_b32_e32 v27, v12
	v_mov_b32_e32 v12, v11
	s_waitcnt lgkmcnt(6)
	v_pk_mul_f32 v[10:11], v[20:21], v[16:17]
	s_waitcnt lgkmcnt(4)
	v_pk_mul_f32 v[20:21], v[28:29], v[56:57]
	s_waitcnt lgkmcnt(2)
	v_pk_mul_f32 v[16:17], v[24:25], v[54:55]
	v_cndmask_b32_e64 v21, v21, -v21, vcc
	v_cndmask_b32_e64 v20, v20, -v20, vcc
	s_waitcnt lgkmcnt(0)
	v_pk_mul_f32 v[12:13], v[12:13], v[58:59]
	v_cndmask_b32_e64 v11, v11, -v11, vcc
	v_cndmask_b32_e64 v10, v10, -v10, vcc
	v_cndmask_b32_e64 v17, v17, -v17, vcc
	v_cndmask_b32_e64 v16, v16, -v16, vcc
	v_pk_fma_f32 v[14:15], v[22:23], v[14:15], v[20:21]
	v_cndmask_b32_e64 v13, v13, -v13, vcc
	v_cndmask_b32_e64 v12, v12, -v12, vcc
	v_pk_fma_f32 v[10:11], v[60:61], v[34:35], v[10:11]
	v_pk_fma_f32 v[16:17], v[18:19], v[36:37], v[16:17]
	v_pk_fma_f32 v[26:27], v[26:27], v[52:53], v[12:13]
	global_load_dwordx4 v[52:55], v[32:33], off offset:48
	global_load_dwordx4 v[56:59], v[32:33], off offset:32
	v_add_u32_e32 v60, s3, v126
	v_mov_b32_e32 v76, v14
	v_ashrrev_i32_e32 v61, 31, v60
	v_add_u32_e32 v18, 0x200, v50
	v_mov_b32_e32 v77, v15
	v_lshlrev_b64 v[14:15], 11, v[60:61]
	v_ashrrev_i32_e32 v128, 3, v18
	v_mov_b32_e32 v72, v10
	v_mov_b32_e32 v73, v11
	v_mov_b32_e32 v78, v26
	v_lshl_add_u64 v[10:11], s[62:63], 0, v[14:15]
	v_lshlrev_b32_e32 v12, 4, v50
	v_add_u32_e32 v62, s3, v128
	v_lshl_add_u64 v[10:11], v[10:11], 0, s[34:35]
	v_and_b32_e32 v114, 0x70, v12
	v_lshl_add_u64 v[14:15], s[64:65], 0, v[14:15]
	v_ashrrev_i32_e32 v63, 31, v62
	v_lshl_add_u64 v[10:11], v[10:11], 0, v[114:115]
	v_lshl_add_u64 v[14:15], v[14:15], 0, s[34:35]
	v_lshlrev_b64 v[22:23], 11, v[62:63]
	v_mov_b32_e32 v75, v17
	global_load_dwordx4 v[10:13], v[10:11], off
	v_lshl_add_u64 v[14:15], v[14:15], 0, v[114:115]
	v_lshl_add_u64 v[18:19], s[62:63], 0, v[22:23]
	v_mov_b32_e32 v74, v16
	global_load_dwordx4 v[14:17], v[14:15], off
	v_lshl_add_u64 v[18:19], v[18:19], 0, s[34:35]
	v_lshl_add_u64 v[22:23], s[64:65], 0, v[22:23]
	v_lshl_add_u64 v[18:19], v[18:19], 0, v[114:115]
	v_lshl_add_u64 v[22:23], v[22:23], 0, s[34:35]
	v_lshlrev_b32_e32 v26, 3, v50
	global_load_dwordx4 v[18:21], v[18:19], off
	v_lshl_add_u64 v[22:23], v[22:23], 0, v[114:115]
	global_load_dwordx4 v[22:25], v[22:23], off
	v_lshlrev_b64 v[28:29], 6, v[64:65]
	v_and_b32_e32 v130, 24, v26
	v_lshl_add_u64 v[28:29], s[42:43], 0, v[28:29]
	v_lshlrev_b32_e32 v116, 1, v130
	v_lshl_add_u64 v[28:29], v[28:29], 0, v[116:117]
	global_load_dwordx4 v[34:37], v[28:29], off
	v_mov_b32_e32 v61, v27
	global_load_dwordx4 v[26:29], v[30:31], off
	s_nop 0
	global_load_dwordx4 v[30:33], v[30:31], off offset:64
	s_waitcnt vmcnt(11)
	v_and_b32_e32 v67, 0xffff0000, v38
	v_lshlrev_b32_e32 v66, 16, v38
	ds_bpermute_b32 v68, v124, v66
	ds_bpermute_b32 v69, v124, v67
	s_waitcnt vmcnt(9)
	v_mov_b32_e32 v71, v48
	v_mov_b32_e32 v48, v47
	v_mov_b32_e32 v70, v46
	v_lshl_add_u64 v[122:123], s[42:43], 0, v[116:117]
	s_waitcnt lgkmcnt(0)
	v_pk_mul_f32 v[46:47], v[48:49], v[68:69]
	v_and_b32_e32 v49, 0xffff0000, v39
	v_lshlrev_b32_e32 v48, 16, v39
	ds_bpermute_b32 v38, v124, v48
	ds_bpermute_b32 v39, v124, v49
	v_cndmask_b32_e64 v47, v47, -v47, vcc
	v_cndmask_b32_e64 v46, v46, -v46, vcc
	v_pk_fma_f32 v[46:47], v[70:71], v[66:67], v[46:47]
	v_mov_b32_e32 v66, v42
	v_mov_b32_e32 v67, v44
	v_mov_b32_e32 v44, v43
	v_and_b32_e32 v43, 0xffff0000, v40
	v_lshlrev_b32_e32 v42, 16, v40
	s_waitcnt lgkmcnt(0)
	v_pk_mul_f32 v[38:39], v[44:45], v[38:39]
	ds_bpermute_b32 v44, v124, v42
	ds_bpermute_b32 v45, v124, v43
	v_cndmask_b32_e64 v39, v39, -v39, vcc
	v_cndmask_b32_e64 v38, v38, -v38, vcc
	v_pk_fma_f32 v[38:39], v[66:67], v[48:49], v[38:39]
	v_add_u32_e32 v137, 0x80, v60
	v_or_b32_e32 v133, 0xd000, v130
	v_or_b32_e32 v134, 0xd020, v130
	s_waitcnt vmcnt(7)
	v_mov_b32_e32 v49, v58
	v_mov_b32_e32 v58, v57
	s_waitcnt lgkmcnt(0)
	v_pk_mul_f32 v[44:45], v[58:59], v[44:45]
	v_mov_b32_e32 v48, v56
	v_cndmask_b32_e64 v45, v45, -v45, vcc
	v_cndmask_b32_e64 v44, v44, -v44, vcc
	v_pk_fma_f32 v[42:43], v[48:49], v[42:43], v[44:45]
	v_mov_b32_e32 v44, v52
	v_mov_b32_e32 v45, v54
	v_mov_b32_e32 v54, v53
	v_and_b32_e32 v57, 0xffff0000, v41
	v_lshlrev_b32_e32 v56, 16, v41
	v_mov_b32_e32 v53, v38
	v_mov_b32_e32 v52, v39
	v_mad_u64_u32 v[38:39], s[2:3], v126, s12, v[114:115]
	ds_bpermute_b32 v40, v124, v56
	ds_bpermute_b32 v41, v124, v57
	v_lshlrev_b32_e32 v39, 6, v126
	s_waitcnt lgkmcnt(0)
	v_pk_mul_f32 v[40:41], v[54:55], v[40:41]
	v_cndmask_b32_e64 v41, v41, -v41, vcc
	v_cndmask_b32_e64 v40, v40, -v40, vcc
	s_waitcnt vmcnt(6)
	ds_write_b128 v38, v[10:13]
	v_sub_u32_e32 v38, v38, v39
	v_pk_fma_f32 v[40:41], v[44:45], v[56:57], v[40:41]
	v_cmp_lt_i32_e32 vcc, v197, v196
	s_waitcnt vmcnt(5)
	ds_write_b128 v38, v[14:17] offset:53248
	v_mad_u64_u32 v[38:39], s[2:3], v128, s12, v[114:115]
	v_lshlrev_b32_e32 v39, 6, v128
	s_waitcnt vmcnt(4)
	ds_write_b128 v38, v[18:21]
	v_sub_u32_e32 v38, v38, v39
	s_waitcnt vmcnt(3)
	ds_write_b128 v38, v[22:25] offset:53248
	v_mad_u64_u32 v[38:39], s[2:3], v129, s12, v[116:117]
	s_add_u32 s2, s62, s34
	s_addc_u32 s3, s63, 0
	s_waitcnt vmcnt(2)
	ds_write_b128 v38, v[34:37] offset:128
	v_cndmask_b32_e32 v38, v195, v197, vcc
	v_lshl_add_u64 v[118:119], s[2:3], 0, v[114:115]
	s_add_u32 s2, s64, s34
	v_mov_b32_e32 v45, v40
	v_mov_b32_e32 v44, v41
	v_lshlrev_b32_e32 v127, 2, v38
	v_bfe_u32 v38, v50, 2, 2
	s_addc_u32 s3, s65, 0
	v_mov_b32_e32 v48, v1
	v_mov_b32_e32 v49, v1
	v_or_b32_e32 v132, v131, v38
	v_cvt_pk_bf16_f32 v41, v78, v61
	v_cvt_pk_bf16_f32 v40, v76, v77
	v_cvt_pk_bf16_f32 v39, v74, v75
	v_cvt_pk_bf16_f32 v38, v72, v73
	v_cvt_pk_bf16_f32 v45, v45, v44
	v_cvt_pk_bf16_f32 v44, v42, v43
	v_cvt_pk_bf16_f32 v43, v53, v52
	v_cvt_pk_bf16_f32 v42, v46, v47
	v_lshl_add_u64 v[120:121], s[2:3], 0, v[114:115]
	v_add_u32_e32 v115, 0x80, v64
	v_add_u32_e32 v117, 0x80, v62
	v_mov_b32_e32 v46, v1
	v_mov_b32_e32 v47, v1
	v_mov_b64_e32 v[64:65], v[48:49]
	v_mov_b64_e32 v[52:53], v[48:49]
	v_mov_b64_e32 v[68:69], v[48:49]
	v_mov_b64_e32 v[56:57], v[48:49]
	v_mov_b64_e32 v[72:73], v[48:49]
	v_mov_b64_e32 v[60:61], v[48:49]
	v_mov_b64_e32 v[76:77], v[48:49]
	v_or_b32_e32 v135, 0xd040, v130
	v_or_b32_e32 v136, 0xd060, v130
	v_mov_b64_e32 v[62:63], v[46:47]
	v_mov_b64_e32 v[50:51], v[46:47]
	v_mov_b64_e32 v[66:67], v[46:47]
	v_mov_b64_e32 v[54:55], v[46:47]
	v_mov_b64_e32 v[70:71], v[46:47]
	v_mov_b64_e32 v[58:59], v[46:47]
	v_mov_b64_e32 v[74:75], v[46:47]
	s_waitcnt vmcnt(0)
	s_waitcnt lgkmcnt(0)
	s_barrier
	s_branch .LBB0_574

.LBB0_576:
	s_and_b32 s5, s7, 0x80
	v_or_b32_e32 v142, s5, v125
	v_mad_u32_u24 v143, v142, s12, v0
	ds_read_b128 v[78:81], v143
	ds_read_b128 v[82:85], v143 offset:64
	ds_read_b128 v[86:89], v143 offset:128
	ds_read_b128 v[94:97], v143 offset:3328
	ds_read_b128 v[98:101], v143 offset:3392
	ds_read_b128 v[144:147], v143 offset:3456
	s_setprio 1
	s_waitcnt lgkmcnt(5)
	v_mfma_f32_16x16x32_bf16 v[90:93], v[78:81], v[2:5], 0
	v_mfma_f32_16x16x32_bf16 v[78:81], v[78:81], v[26:29], 0
	s_waitcnt lgkmcnt(4)
	v_mfma_f32_16x16x32_bf16 v[90:93], v[82:85], v[6:9], v[90:93]
	v_mfma_f32_16x16x32_bf16 v[78:81], v[82:85], v[30:33], v[78:81]
	s_waitcnt lgkmcnt(3)
	v_mfma_f32_16x16x32_bf16 v[106:109], v[86:89], v[38:41], v[90:93]
	v_mfma_f32_16x16x32_bf16 v[90:93], v[86:89], v[42:45], v[78:81]
	s_waitcnt lgkmcnt(2)
	v_mfma_f32_16x16x32_bf16 v[78:81], v[94:97], v[2:5], 0
	v_mfma_f32_16x16x32_bf16 v[82:85], v[94:97], v[26:29], 0
	s_waitcnt lgkmcnt(1)
	v_mfma_f32_16x16x32_bf16 v[78:81], v[98:101], v[6:9], v[78:81]
	v_mfma_f32_16x16x32_bf16 v[82:85], v[98:101], v[30:33], v[82:85]
	s_waitcnt lgkmcnt(0)
	v_mfma_f32_16x16x32_bf16 v[102:105], v[144:147], v[38:41], v[78:81]
	v_mfma_f32_16x16x32_bf16 v[82:85], v[144:147], v[42:45], v[82:85]
	s_setprio 0
	s_nop 2
	ds_read_b128 v[78:81], v143 offset:6656
	ds_read_b128 v[86:89], v143 offset:6720
	ds_read_b128 v[94:97], v143 offset:6784
	ds_read_b128 v[144:147], v143 offset:9984
	ds_read_b128 v[148:151], v143 offset:10048
	ds_read_b128 v[152:155], v143 offset:10112
	s_setprio 1
	s_waitcnt lgkmcnt(5)
	v_mfma_f32_16x16x32_bf16 v[98:101], v[78:81], v[2:5], 0
	v_mfma_f32_16x16x32_bf16 v[78:81], v[78:81], v[26:29], 0
	s_waitcnt lgkmcnt(4)
	v_mfma_f32_16x16x32_bf16 v[98:101], v[86:89], v[6:9], v[98:101]
	v_mfma_f32_16x16x32_bf16 v[78:81], v[86:89], v[30:33], v[78:81]
	s_waitcnt lgkmcnt(3)
	v_mfma_f32_16x16x32_bf16 v[98:101], v[94:97], v[38:41], v[98:101]
	v_mfma_f32_16x16x32_bf16 v[86:89], v[94:97], v[42:45], v[78:81]
	s_waitcnt lgkmcnt(2)
	v_mfma_f32_16x16x32_bf16 v[78:81], v[144:147], v[2:5], 0
	v_mfma_f32_16x16x32_bf16 v[94:97], v[144:147], v[26:29], 0
	s_waitcnt lgkmcnt(1)
	v_mfma_f32_16x16x32_bf16 v[78:81], v[148:151], v[6:9], v[78:81]
	v_mfma_f32_16x16x32_bf16 v[144:147], v[148:151], v[30:33], v[94:97]
	s_waitcnt lgkmcnt(0)
	v_mfma_f32_16x16x32_bf16 v[94:97], v[152:155], v[38:41], v[78:81]
	v_mfma_f32_16x16x32_bf16 v[78:81], v[152:155], v[42:45], v[144:147]
	s_setprio 0
	v_max3_f32 v143, v106, s18, v107
	v_max3_f32 v143, v143, v108, v109
	v_max3_f32 v143, v143, v102, v103
	v_max3_f32 v143, v143, v104, v105
	v_max3_f32 v143, v143, v98, v99
	v_max3_f32 v143, v143, v100, v101
	v_max3_f32 v143, v143, v94, v95
	v_max3_f32 v143, v143, v96, v97
	v_mul_f32_e32 v143, 0x3e16c740, v143
	ds_bpermute_b32 v144, v124, v143
	s_waitcnt lgkmcnt(0)
	v_max_f32_e32 v144, v144, v144
	v_max_f32_e32 v143, v143, v144
	ds_bpermute_b32 v144, v127, v143
	s_waitcnt lgkmcnt(0)
	v_max_f32_e32 v144, v144, v144
	v_max_f32_e32 v143, v143, v144
	v_add_f32_e32 v144, 0x41000000, v139
	v_cmp_gt_f32_e32 vcc, v143, v144
	s_cbranch_vccz .LBB0_578
	v_max_f32_e32 v143, v143, v143
	v_max_f32_e32 v144, v139, v139
	v_max_f32_e32 v143, v144, v143
	v_sub_f32_e32 v139, v139, v143
	v_exp_f32_e32 v144, v139
	v_mov_b32_e32 v139, v143
	v_mul_f32_e32 v141, v141, v144
	v_pk_mul_f32 v[76:77], v[76:77], v[144:145] op_sel_hi:[1,0]
	v_pk_mul_f32 v[74:75], v[74:75], v[144:145] op_sel_hi:[1,0]
	v_pk_mul_f32 v[72:73], v[72:73], v[144:145] op_sel_hi:[1,0]
	v_pk_mul_f32 v[70:71], v[70:71], v[144:145] op_sel_hi:[1,0]
	v_pk_mul_f32 v[68:69], v[68:69], v[144:145] op_sel_hi:[1,0]
	v_pk_mul_f32 v[66:67], v[66:67], v[144:145] op_sel_hi:[1,0]
	v_pk_mul_f32 v[64:65], v[64:65], v[144:145] op_sel_hi:[1,0]
	v_pk_mul_f32 v[62:63], v[62:63], v[144:145] op_sel_hi:[1,0]

.LBB0_586:
	v_lshl_add_u32 v180, v143, 1, v210
	v_fmamk_f32 v106, v106, 0x3e16c740, v160
	v_fmamk_f32 v107, v107, 0x3e16c740, v160
	v_fmamk_f32 v108, v108, 0x3e16c740, v160
	v_fmamk_f32 v109, v109, 0x3e16c740, v160
	v_fmamk_f32 v98, v98, 0x3e16c740, v160
	v_fmamk_f32 v99, v99, 0x3e16c740, v160
	v_fmamk_f32 v100, v100, 0x3e16c740, v160
	v_fmamk_f32 v101, v101, 0x3e16c740, v160
	v_fmamk_f32 v102, v102, 0x3e16c740, v160
	v_fmamk_f32 v103, v103, 0x3e16c740, v160
	v_fmamk_f32 v104, v104, 0x3e16c740, v160
	v_fmamk_f32 v105, v105, 0x3e16c740, v160
	v_fmamk_f32 v94, v94, 0x3e16c740, v160
	v_fmamk_f32 v95, v95, 0x3e16c740, v160
	v_fmamk_f32 v96, v96, 0x3e16c740, v160
	v_fmac_f32_e32 v160, 0x3e16c740, v97
	v_fmamk_f32 v90, v90, 0x3e16c740, v144
	v_fmamk_f32 v91, v91, 0x3e16c740, v144
	v_fmamk_f32 v92, v92, 0x3e16c740, v144
	v_fmamk_f32 v93, v93, 0x3e16c740, v144
	v_fmamk_f32 v82, v82, 0x3e16c740, v144
	v_fmamk_f32 v83, v83, 0x3e16c740, v144
	v_fmamk_f32 v84, v84, 0x3e16c740, v144
	v_fmamk_f32 v85, v85, 0x3e16c740, v144
	v_fmamk_f32 v86, v86, 0x3e16c740, v144
	v_fmamk_f32 v87, v87, 0x3e16c740, v144
	v_fmamk_f32 v88, v88, 0x3e16c740, v144
	v_fmamk_f32 v89, v89, 0x3e16c740, v144
	v_fmamk_f32 v78, v78, 0x3e16c740, v144
	v_fmamk_f32 v79, v79, 0x3e16c740, v144
	v_fmamk_f32 v80, v80, 0x3e16c740, v144
	v_fmac_f32_e32 v144, 0x3e16c740, v81
	v_add_u32_e32 v143, v133, v180
	v_exp_f32_e32 v97, v160
	v_exp_f32_e32 v81, v144
	ds_read_b64_tr_b16 v[160:161], v142 offset:64768
	ds_read_b64_tr_b16 v[158:159], v142 offset:62464
	ds_read_b64_tr_b16 v[166:167], v142 offset:64800
	ds_read_b64_tr_b16 v[164:165], v142 offset:62496
	v_add_u32_e32 v144, v134, v180
	ds_read_b64_tr_b16 v[168:169], v143
	ds_read_b64_tr_b16 v[170:171], v143 offset:2304
	ds_read_b64_tr_b16 v[172:173], v144
	ds_read_b64_tr_b16 v[174:175], v144 offset:2304
	v_exp_f32_e32 v106, v106
	v_exp_f32_e32 v107, v107
	v_exp_f32_e32 v108, v108
	v_exp_f32_e32 v109, v109
	v_exp_f32_e32 v98, v98
	v_exp_f32_e32 v99, v99
	v_exp_f32_e32 v100, v100
	v_exp_f32_e32 v101, v101
	v_exp_f32_e32 v102, v102
	v_exp_f32_e32 v103, v103
	v_exp_f32_e32 v104, v104
	v_exp_f32_e32 v105, v105
	v_exp_f32_e32 v94, v94
	v_exp_f32_e32 v95, v95
	v_exp_f32_e32 v96, v96
	v_exp_f32_e32 v90, v90
	v_exp_f32_e32 v91, v91
	v_exp_f32_e32 v92, v92
	v_exp_f32_e32 v93, v93
	v_exp_f32_e32 v82, v82
	v_exp_f32_e32 v83, v83
	v_exp_f32_e32 v84, v84
	v_exp_f32_e32 v85, v85
	v_exp_f32_e32 v86, v86
	v_exp_f32_e32 v87, v87
	v_exp_f32_e32 v88, v88
	v_exp_f32_e32 v89, v89
	v_exp_f32_e32 v78, v78
	v_exp_f32_e32 v79, v79
	v_exp_f32_e32 v80, v80
	v_cvt_pk_bf16_f32 v146, v106, v107
	v_cvt_pk_bf16_f32 v147, v108, v109
	v_cvt_pk_bf16_f32 v148, v98, v99
	v_cvt_pk_bf16_f32 v149, v100, v101
	v_cvt_pk_bf16_f32 v150, v102, v103
	v_cvt_pk_bf16_f32 v151, v104, v105
	v_cvt_pk_bf16_f32 v152, v94, v95
	v_cvt_pk_bf16_f32 v153, v96, v97
	v_cvt_pk_bf16_f32 v154, v90, v91
	v_cvt_pk_bf16_f32 v155, v92, v93
	v_cvt_pk_bf16_f32 v156, v82, v83
	v_cvt_pk_bf16_f32 v157, v84, v85
	v_cvt_pk_bf16_f32 v176, v86, v87
	v_cvt_pk_bf16_f32 v177, v88, v89
	v_cvt_pk_bf16_f32 v178, v78, v79
	v_cvt_pk_bf16_f32 v179, v80, v81
	s_setprio 1
	s_waitcnt lgkmcnt(6)
	v_mfma_f32_16x16x32_bf16 v[74:77], v[158:161], v[146:149], v[74:77]
	v_mfma_f32_16x16x32_bf16 v[58:61], v[158:161], v[154:157], v[58:61]
	s_waitcnt lgkmcnt(4)
	v_mfma_f32_16x16x32_bf16 v[54:57], v[164:167], v[146:149], v[54:57]
	v_mfma_f32_16x16x32_bf16 v[158:161], v[164:167], v[154:157], v[70:73]
	s_waitcnt lgkmcnt(2)
	v_mfma_f32_16x16x32_bf16 v[74:77], v[168:171], v[150:153], v[74:77]
	v_mfma_f32_16x16x32_bf16 v[58:61], v[168:171], v[176:179], v[58:61]
	s_waitcnt lgkmcnt(0)
	v_mfma_f32_16x16x32_bf16 v[70:73], v[172:175], v[150:153], v[54:57]
	v_mfma_f32_16x16x32_bf16 v[54:57], v[172:175], v[176:179], v[158:161]
	s_setprio 0
	v_add_u32_e32 v166, v135, v180
	v_add_u32_e32 v170, v136, v180
	ds_read_b64_tr_b16 v[160:161], v142 offset:64832
	ds_read_b64_tr_b16 v[158:159], v142 offset:62528
	ds_read_b64_tr_b16 v[144:145], v142 offset:64864
	ds_read_b64_tr_b16 v[142:143], v142 offset:62560
	ds_read_b64_tr_b16 v[164:165], v166
	ds_read_b64_tr_b16 v[166:167], v166 offset:2304
	ds_read_b64_tr_b16 v[168:169], v170
	ds_read_b64_tr_b16 v[170:171], v170 offset:2304
	s_setprio 1
	s_waitcnt lgkmcnt(6)
	v_mfma_f32_16x16x32_bf16 v[50:53], v[158:161], v[146:149], v[50:53]
	v_mfma_f32_16x16x32_bf16 v[158:161], v[158:161], v[154:157], v[66:69]
	s_waitcnt lgkmcnt(4)
	v_mfma_f32_16x16x32_bf16 v[46:49], v[142:145], v[146:149], v[46:49]
	v_mfma_f32_16x16x32_bf16 v[142:145], v[142:145], v[154:157], v[62:65]
	s_waitcnt lgkmcnt(2)
	v_mfma_f32_16x16x32_bf16 v[66:69], v[164:167], v[150:153], v[50:53]
	v_mfma_f32_16x16x32_bf16 v[50:53], v[164:167], v[176:179], v[158:161]
	s_waitcnt lgkmcnt(0)
	v_mfma_f32_16x16x32_bf16 v[62:65], v[168:171], v[150:153], v[46:49]
	v_mfma_f32_16x16x32_bf16 v[46:49], v[168:171], v[176:179], v[142:145]
	s_setprio 0
	s_andn2_b64 vcc, exec, s[2:3]
	s_cbranch_vccnz .LBB0_573
	s_xor_b32 s5, s5, 0x80
	v_add_u32_e32 v144, s5, v126
	v_mad_u64_u32 v[142:143], s[2:3], v144, s12, v[114:115]
	s_waitcnt vmcnt(4)
	ds_write_b128 v142, v[10:13]
	v_mad_u64_u32 v[142:143], s[2:3], v144, s16, v[114:115]
	v_add_u32_e32 v144, s5, v128
	s_waitcnt vmcnt(3)
	ds_write_b128 v142, v[14:17] offset:53248
	v_mad_u64_u32 v[142:143], s[2:3], v144, s12, v[114:115]
	s_waitcnt vmcnt(2)
	ds_write_b128 v142, v[18:21]
	v_mad_u64_u32 v[142:143], s[2:3], v144, s16, v[114:115]
	s_waitcnt vmcnt(1)
	ds_write_b128 v142, v[22:25] offset:53248
	v_add_u32_e32 v142, s5, v129
	v_mad_u64_u32 v[142:143], s[2:3], v142, s12, v[116:117]
	s_waitcnt vmcnt(0)
	ds_write_b128 v142, v[34:37] offset:128
	s_branch .LBB0_573
